# speedup vs baseline: 1.0172x; 1.0172x over previous
; #define WAIT_V(n) asm volatile("s_waitcnt vmcnt(" #n ")" ::: "memory")
; __device__ __forceinline__ void gemm_run(const Params& p, const u16* A1, const u16* Bt1, int M1, int N1, int K, int mode1,
;                                          const float* resid, u16* shm, const u16* A2, const u16* Bt2, int M2, int N2,
;                                          int mode2) {
;     ...
;     WAIT_V(0);
;   }
.LBB0_382:
	s_add_i32 s89, s89, s94
	s_cmp_lt_i32 s89, s64
	s_cbranch_scc0 .LBB0_1268

; __device__ __forceinline__ void epilogue(const Params& p, int mode, const float* resid, int r, int c, f32x4 v) {
;   if (mode == EPI_PROJ) {
;     if (r >= INW) return;
;     u32x2 pk = {pk2(v[0], v[1]), pk2(v[2], v[3])};
;     *reinterpret_cast<u32x2*>(WSP(u16, WS_PROJB) + (long)c * INWP + r) = pk;
;   } else if (mode == EPI_PROJ_T) {
;     const int b = r >> 11, t = r & 2047;
;     u16* tp;
;     if (c < OFF_RG) tp = WSP(u16, WS_RVT) + ((long)(b * 2048 + c - OFF_RV)) * 2048 + t;
;     else if (c < OFF_KW) tp = WSP(u16, WS_VST) + ((long)(b * 512 + c - OFF_VS)) * 2048 + t;
;     else tp = WSP(u16, WS_VWT) + ((long)(b * 512 + c - OFF_VW)) * 2048 + t;
;     *reinterpret_cast<u32x2*>(tp) = u32x2{pk2(v[0], v[1]), pk2(v[2], v[3])};
.LBB0_404:
	s_or_b64 exec, exec, s[0:1]
	v_add_u32_e32 v190, s74, v187
	v_lshlrev_b32_e32 v0, 1, v190
	v_and_b32_e32 v0, 0xfffffe00, v0
	v_add_u32_e32 v194, 0xfffffe00, v0
	v_ashrrev_i32_e32 v0, 2, v190
	v_and_b32_e32 v0, 0xfffffe00, v0
	v_add_u32_e32 v192, 0xffffce00, v0
	v_add_u32_e32 v193, 0xffffd200, v0
	v_and_b32_e32 v0, 0xfffff800, v190
	s_movk_i32 s0, 0xcc
	v_add_u32_e32 v191, 0xfffff000, v0
	v_bitop3_b32 v0, v190, s0, v188 bitop3:0xc8
	v_or_b32_e32 v164, v190, v188
	v_lshlrev_b32_e32 v0, 1, v0
	s_movk_i32 s0, 0x7cc
	v_ashrrev_i32_e32 v165, 31, v164
	v_lshl_add_u64 v[152:153], s[44:45], 0, v[0:1]
	v_bitop3_b32 v0, v190, s0, v188 bitop3:0xc8
	v_lshlrev_b64 v[144:145], 1, v[164:165]
	v_lshlrev_b64 v[136:137], 2, v[164:165]
	v_lshlrev_b32_e32 v0, 1, v0
	v_lshl_add_u64 v[138:139], s[36:37], 0, v[144:145]
	v_lshl_add_u64 v[142:143], s[40:41], 0, v[144:145]
	v_lshl_add_u64 v[140:141], s[42:43], 0, v[136:137]
	v_lshl_add_u64 v[148:149], s[48:49], 0, v[0:1]
	v_lshl_add_u64 v[150:151], s[50:51], 0, v[0:1]
	v_lshl_add_u64 v[146:147], s[52:53], 0, v[0:1]
	v_cmp_gt_i32_e64 s[8:9], s23, v164
	v_or_b32_e32 v130, s91, v189
	s_cmp_eq_u32 s90, 4
	s_cbranch_scc1 .Lepi4_start
	s_cmp_eq_u32 s90, 6
	s_cbranch_scc1 .Lepi6_start
	s_cmp_lg_u32 s90, 0
	s_cbranch_scc1 .Lepi0_skip
	s_cmpk_lg_u32 s74, 0x3400
	s_cbranch_scc1 .Lepi0_start
.Lepi0_skip:
	s_cmp_eq_u32 s90, 5
	s_cbranch_scc1 .Lepi5_start
	s_cmp_eq_u32 s90, 2
	s_cbranch_scc1 .Lepi2_start
	s_cmp_lt_i32 s90, 4
	s_mov_b64 s[0:1], -1
	s_cbranch_scc1 .LBB0_417
	s_cmp_lt_i32 s90, 6
	s_cbranch_scc1 .LBB0_411
	s_cmp_gt_i32 s90, 6
	s_cbranch_scc0 .LBB0_408
	v_add_u32_e32 v156, v194, v130
	v_ashrrev_i32_e32 v157, 31, v156
	v_lshlrev_b64 v[156:157], 9, v[156:157]
	v_lshl_add_u64 v[156:157], v[152:153], 0, v[156:157]
	v_cvt_pk_bf16_f32 v154,v126,v127
	v_cvt_pk_bf16_f32 v155,v128,v129
	flat_store_dwordx2 v[156:157], v[154:155]
	s_mov_b64 s[0:1], 0

; __device__ __forceinline__ void epilogue(const Params& p, int mode, const float* resid, int r, int c, f32x4 v) {
;     ...
;     float a0 = fmaxf(v[0], 0.f), a1 = fmaxf(v[1], 0.f), a2 = fmaxf(v[2], 0.f), a3 = fmaxf(v[3], 0.f);
;     u32x2 pk = {pk2(a0 * a0, a1 * a1), pk2(a2 * a2, a3 * a3)};
;     *reinterpret_cast<u32x2*>(WSP(u16, WS_ACT) + (long)c * DFF + r) = pk;
; __device__ __forceinline__ void gemm_run(const Params& p, const u16* A1, const u16* Bt1, int M1, int N1, int K, int mode1,
;                                          const float* resid, u16* shm, const u16* A2, const u16* Bt2, int M2, int N2,
;                                          int mode2) {
;     ...
; #pragma unroll
;     for (int ai = 0; ai < 2; ++ai)
; #pragma unroll
;       for (int bj = 0; bj < 2; ++bj)
; #pragma unroll
;         for (int m = 0; m < 4; ++m)
; #pragma unroll
;           for (int n = 0; n < 2; ++n)
;             epilogue(p, mode, resid, brow + ai * HALF + wr * 64 + m * 16 + fq * 4, bcol + bj * HALF + wc * 32 + n * 16 + fr,
;                      acc[ai][bj][m][n]);
.Lepi4_start:
	v_lshrrev_b32_e32 v0, 2, v188
	v_lshrrev_b32_e32 v130, 2, v187
	v_or_b32_e32 v0, v0, v130
	v_and_b32_e32 v130, 15, v189
	v_lshlrev_b32_e32 v130, 1, v130
	v_xor_b32_e32 v0, v0, v130
	v_lshlrev_b32_e32 v0, 3, v0
	v_lshlrev_b32_e32 v131, 9, v189
	v_or_b32_e32 v136, v131, v0
	v_add_u32_e32 v136, 64, v136
	v_add_u32_e32 v140, 0x10000, v136
	v_xor_b32_e32 v130, 32, v0
	v_or_b32_e32 v137, v131, v130
	v_add_u32_e32 v137, 64, v137
	v_add_u32_e32 v141, 0x10000, v137
	v_xor_b32_e32 v130, 64, v0
	v_or_b32_e32 v138, v131, v130
	v_add_u32_e32 v138, 64, v138
	v_add_u32_e32 v142, 0x10000, v138
	v_xor_b32_e32 v130, 96, v0
	v_or_b32_e32 v139, v131, v130
	v_add_u32_e32 v139, 64, v139
	v_add_u32_e32 v143, 0x10000, v139
	v_max_f32_e32 v126, 0, v126
	v_max_f32_e32 v127, 0, v127
	v_max_f32_e32 v128, 0, v128
	v_max_f32_e32 v129, 0, v129
	v_pk_mul_f32 v[126:127], v[126:127], v[126:127]
	v_pk_mul_f32 v[128:129], v[128:129], v[128:129]
	v_cvt_pk_bf16_f32 v126, v126, v127
	v_cvt_pk_bf16_f32 v127, v128, v129
	ds_write_b64 v136, v[126:127] offset:0
	v_max_f32_e32 v122, 0, v122
	v_max_f32_e32 v123, 0, v123
	v_max_f32_e32 v124, 0, v124
	v_max_f32_e32 v125, 0, v125
	v_pk_mul_f32 v[122:123], v[122:123], v[122:123]
	v_pk_mul_f32 v[124:125], v[124:125], v[124:125]
	v_cvt_pk_bf16_f32 v122, v122, v123
	v_cvt_pk_bf16_f32 v123, v124, v125
	ds_write_b64 v136, v[122:123] offset:8192
	v_max_f32_e32 v118, 0, v118
	v_max_f32_e32 v119, 0, v119
	v_max_f32_e32 v120, 0, v120
	v_max_f32_e32 v121, 0, v121
	v_pk_mul_f32 v[118:119], v[118:119], v[118:119]
	v_pk_mul_f32 v[120:121], v[120:121], v[120:121]
	v_cvt_pk_bf16_f32 v118, v118, v119
	v_cvt_pk_bf16_f32 v119, v120, v121
	ds_write_b64 v137, v[118:119] offset:0
	v_max_f32_e32 v114, 0, v114
	v_max_f32_e32 v115, 0, v115
	v_max_f32_e32 v116, 0, v116
	v_max_f32_e32 v117, 0, v117
	v_pk_mul_f32 v[114:115], v[114:115], v[114:115]
	v_pk_mul_f32 v[116:117], v[116:117], v[116:117]
	v_cvt_pk_bf16_f32 v114, v114, v115
	v_cvt_pk_bf16_f32 v115, v116, v117
	ds_write_b64 v137, v[114:115] offset:8192
	v_max_f32_e32 v110, 0, v110
	v_max_f32_e32 v111, 0, v111
	v_max_f32_e32 v112, 0, v112
	v_max_f32_e32 v113, 0, v113
	v_pk_mul_f32 v[110:111], v[110:111], v[110:111]
	v_pk_mul_f32 v[112:113], v[112:113], v[112:113]
	v_cvt_pk_bf16_f32 v110, v110, v111
	v_cvt_pk_bf16_f32 v111, v112, v113
	ds_write_b64 v138, v[110:111] offset:0
	v_max_f32_e32 v106, 0, v106
	v_max_f32_e32 v107, 0, v107
	v_max_f32_e32 v108, 0, v108
	v_max_f32_e32 v109, 0, v109
	v_pk_mul_f32 v[106:107], v[106:107], v[106:107]
	v_pk_mul_f32 v[108:109], v[108:109], v[108:109]
	v_cvt_pk_bf16_f32 v106, v106, v107
	v_cvt_pk_bf16_f32 v107, v108, v109
	ds_write_b64 v138, v[106:107] offset:8192
	v_max_f32_e32 v102, 0, v102
	v_max_f32_e32 v103, 0, v103
	v_max_f32_e32 v104, 0, v104
	v_max_f32_e32 v105, 0, v105
	v_pk_mul_f32 v[102:103], v[102:103], v[102:103]
	v_pk_mul_f32 v[104:105], v[104:105], v[104:105]
	v_cvt_pk_bf16_f32 v102, v102, v103
	v_cvt_pk_bf16_f32 v103, v104, v105
	ds_write_b64 v139, v[102:103] offset:0
	v_max_f32_e32 v98, 0, v98
	v_max_f32_e32 v99, 0, v99
	v_max_f32_e32 v100, 0, v100
	v_max_f32_e32 v101, 0, v101
	v_pk_mul_f32 v[98:99], v[98:99], v[98:99]
	v_pk_mul_f32 v[100:101], v[100:101], v[100:101]
	v_cvt_pk_bf16_f32 v98, v98, v99
	v_cvt_pk_bf16_f32 v99, v100, v101
	ds_write_b64 v139, v[98:99] offset:8192
	v_max_f32_e32 v94, 0, v94
	v_max_f32_e32 v95, 0, v95
	v_max_f32_e32 v96, 0, v96
	v_max_f32_e32 v97, 0, v97
	v_pk_mul_f32 v[94:95], v[94:95], v[94:95]
	v_pk_mul_f32 v[96:97], v[96:97], v[96:97]
	v_cvt_pk_bf16_f32 v94, v94, v95
	v_cvt_pk_bf16_f32 v95, v96, v97
	ds_write_b64 v140, v[94:95] offset:0
	v_max_f32_e32 v90, 0, v90
	v_max_f32_e32 v91, 0, v91
	v_max_f32_e32 v92, 0, v92
	v_max_f32_e32 v93, 0, v93
	v_pk_mul_f32 v[90:91], v[90:91], v[90:91]
	v_pk_mul_f32 v[92:93], v[92:93], v[92:93]
	v_cvt_pk_bf16_f32 v90, v90, v91
	v_cvt_pk_bf16_f32 v91, v92, v93
	ds_write_b64 v140, v[90:91] offset:8192
	v_max_f32_e32 v86, 0, v86
	v_max_f32_e32 v87, 0, v87
	v_max_f32_e32 v88, 0, v88
	v_max_f32_e32 v89, 0, v89
	v_pk_mul_f32 v[86:87], v[86:87], v[86:87]
	v_pk_mul_f32 v[88:89], v[88:89], v[88:89]
	v_cvt_pk_bf16_f32 v86, v86, v87
	v_cvt_pk_bf16_f32 v87, v88, v89
	ds_write_b64 v141, v[86:87] offset:0
	v_max_f32_e32 v82, 0, v82
	v_max_f32_e32 v83, 0, v83
	v_max_f32_e32 v84, 0, v84
	v_max_f32_e32 v85, 0, v85
	v_pk_mul_f32 v[82:83], v[82:83], v[82:83]
	v_pk_mul_f32 v[84:85], v[84:85], v[84:85]
	v_cvt_pk_bf16_f32 v82, v82, v83
	v_cvt_pk_bf16_f32 v83, v84, v85
	ds_write_b64 v141, v[82:83] offset:8192
	v_max_f32_e32 v78, 0, v78
	v_max_f32_e32 v79, 0, v79
	v_max_f32_e32 v80, 0, v80
	v_max_f32_e32 v81, 0, v81
	v_pk_mul_f32 v[78:79], v[78:79], v[78:79]
	v_pk_mul_f32 v[80:81], v[80:81], v[80:81]
	v_cvt_pk_bf16_f32 v78, v78, v79
	v_cvt_pk_bf16_f32 v79, v80, v81
	ds_write_b64 v142, v[78:79] offset:0
	v_max_f32_e32 v74, 0, v74
	v_max_f32_e32 v75, 0, v75
	v_max_f32_e32 v76, 0, v76
	v_max_f32_e32 v77, 0, v77
	v_pk_mul_f32 v[74:75], v[74:75], v[74:75]
	v_pk_mul_f32 v[76:77], v[76:77], v[76:77]
	v_cvt_pk_bf16_f32 v74, v74, v75
	v_cvt_pk_bf16_f32 v75, v76, v77
	ds_write_b64 v142, v[74:75] offset:8192
	v_max_f32_e32 v70, 0, v70
	v_max_f32_e32 v71, 0, v71
	v_max_f32_e32 v72, 0, v72
	v_max_f32_e32 v73, 0, v73
	v_pk_mul_f32 v[70:71], v[70:71], v[70:71]
	v_pk_mul_f32 v[72:73], v[72:73], v[72:73]
	v_cvt_pk_bf16_f32 v70, v70, v71
	v_cvt_pk_bf16_f32 v71, v72, v73
	ds_write_b64 v143, v[70:71] offset:0
	v_max_f32_e32 v66, 0, v66
	v_max_f32_e32 v67, 0, v67
	v_max_f32_e32 v68, 0, v68
	v_max_f32_e32 v69, 0, v69
	v_pk_mul_f32 v[66:67], v[66:67], v[66:67]
	v_pk_mul_f32 v[68:69], v[68:69], v[68:69]
	v_cvt_pk_bf16_f32 v66, v66, v67
; __device__ __forceinline__ void epilogue(const Params& p, int mode, const float* resid, int r, int c, f32x4 v) {
;     ...
;     float a0 = fmaxf(v[0], 0.f), a1 = fmaxf(v[1], 0.f), a2 = fmaxf(v[2], 0.f), a3 = fmaxf(v[3], 0.f);
;     u32x2 pk = {pk2(a0 * a0, a1 * a1), pk2(a2 * a2, a3 * a3)};
;     *reinterpret_cast<u32x2*>(WSP(u16, WS_ACT) + (long)c * DFF + r) = pk;
; __device__ __forceinline__ void gemm_run(const Params& p, const u16* A1, const u16* Bt1, int M1, int N1, int K, int mode1,
;                                          const float* resid, u16* shm, const u16* A2, const u16* Bt2, int M2, int N2,
;                                          int mode2) {
;     ...
; #pragma unroll
;     for (int ai = 0; ai < 2; ++ai)
; #pragma unroll
;       for (int bj = 0; bj < 2; ++bj)
; #pragma unroll
;         for (int m = 0; m < 4; ++m)
; #pragma unroll
;           for (int n = 0; n < 2; ++n)
;             epilogue(p, mode, resid, brow + ai * HALF + wr * 64 + m * 16 + fq * 4, bcol + bj * HALF + wc * 32 + n * 16 + fr,
;                      acc[ai][bj][m][n]);
	v_cvt_pk_bf16_f32 v67, v68, v69
	ds_write_b64 v143, v[66:67] offset:8192
	v_max_f32_e32 v62, 0, v62
	v_max_f32_e32 v63, 0, v63
	v_max_f32_e32 v64, 0, v64
	v_max_f32_e32 v65, 0, v65
	v_pk_mul_f32 v[62:63], v[62:63], v[62:63]
	v_pk_mul_f32 v[64:65], v[64:65], v[64:65]
	v_cvt_pk_bf16_f32 v62, v62, v63
	v_cvt_pk_bf16_f32 v63, v64, v65
	ds_write_b64 v136, v[62:63] offset:256
	v_max_f32_e32 v58, 0, v58
	v_max_f32_e32 v59, 0, v59
	v_max_f32_e32 v60, 0, v60
	v_max_f32_e32 v61, 0, v61
	v_pk_mul_f32 v[58:59], v[58:59], v[58:59]
	v_pk_mul_f32 v[60:61], v[60:61], v[60:61]
	v_cvt_pk_bf16_f32 v58, v58, v59
	v_cvt_pk_bf16_f32 v59, v60, v61
	ds_write_b64 v136, v[58:59] offset:8448
	v_max_f32_e32 v54, 0, v54
	v_max_f32_e32 v55, 0, v55
	v_max_f32_e32 v56, 0, v56
	v_max_f32_e32 v57, 0, v57
	v_pk_mul_f32 v[54:55], v[54:55], v[54:55]
	v_pk_mul_f32 v[56:57], v[56:57], v[56:57]
	v_cvt_pk_bf16_f32 v54, v54, v55
	v_cvt_pk_bf16_f32 v55, v56, v57
	ds_write_b64 v137, v[54:55] offset:256
	v_max_f32_e32 v50, 0, v50
	v_max_f32_e32 v51, 0, v51
	v_max_f32_e32 v52, 0, v52
	v_max_f32_e32 v53, 0, v53
	v_pk_mul_f32 v[50:51], v[50:51], v[50:51]
	v_pk_mul_f32 v[52:53], v[52:53], v[52:53]
	v_cvt_pk_bf16_f32 v50, v50, v51
	v_cvt_pk_bf16_f32 v51, v52, v53
	ds_write_b64 v137, v[50:51] offset:8448
	v_max_f32_e32 v46, 0, v46
	v_max_f32_e32 v47, 0, v47
	v_max_f32_e32 v48, 0, v48
	v_max_f32_e32 v49, 0, v49
	v_pk_mul_f32 v[46:47], v[46:47], v[46:47]
	v_pk_mul_f32 v[48:49], v[48:49], v[48:49]
	v_cvt_pk_bf16_f32 v46, v46, v47
	v_cvt_pk_bf16_f32 v47, v48, v49
	ds_write_b64 v138, v[46:47] offset:256
	v_max_f32_e32 v42, 0, v42
	v_max_f32_e32 v43, 0, v43
	v_max_f32_e32 v44, 0, v44
	v_max_f32_e32 v45, 0, v45
	v_pk_mul_f32 v[42:43], v[42:43], v[42:43]
	v_pk_mul_f32 v[44:45], v[44:45], v[44:45]
	v_cvt_pk_bf16_f32 v42, v42, v43
	v_cvt_pk_bf16_f32 v43, v44, v45
	ds_write_b64 v138, v[42:43] offset:8448
	v_max_f32_e32 v38, 0, v38
	v_max_f32_e32 v39, 0, v39
	v_max_f32_e32 v40, 0, v40
	v_max_f32_e32 v41, 0, v41
	v_pk_mul_f32 v[38:39], v[38:39], v[38:39]
	v_pk_mul_f32 v[40:41], v[40:41], v[40:41]
	v_cvt_pk_bf16_f32 v38, v38, v39
	v_cvt_pk_bf16_f32 v39, v40, v41
	ds_write_b64 v139, v[38:39] offset:256
	v_max_f32_e32 v34, 0, v34
	v_max_f32_e32 v35, 0, v35
	v_max_f32_e32 v36, 0, v36
	v_max_f32_e32 v37, 0, v37
	v_pk_mul_f32 v[34:35], v[34:35], v[34:35]
	v_pk_mul_f32 v[36:37], v[36:37], v[36:37]
	v_cvt_pk_bf16_f32 v34, v34, v35
	v_cvt_pk_bf16_f32 v35, v36, v37
	ds_write_b64 v139, v[34:35] offset:8448
	v_max_f32_e32 v30, 0, v30
	v_max_f32_e32 v31, 0, v31
	v_max_f32_e32 v32, 0, v32
	v_max_f32_e32 v33, 0, v33
	v_pk_mul_f32 v[30:31], v[30:31], v[30:31]
	v_pk_mul_f32 v[32:33], v[32:33], v[32:33]
	v_cvt_pk_bf16_f32 v30, v30, v31
	v_cvt_pk_bf16_f32 v31, v32, v33
	ds_write_b64 v140, v[30:31] offset:256
	v_max_f32_e32 v26, 0, v26
	v_max_f32_e32 v27, 0, v27
	v_max_f32_e32 v28, 0, v28
	v_max_f32_e32 v29, 0, v29
	v_pk_mul_f32 v[26:27], v[26:27], v[26:27]
	v_pk_mul_f32 v[28:29], v[28:29], v[28:29]
	v_cvt_pk_bf16_f32 v26, v26, v27
	v_cvt_pk_bf16_f32 v27, v28, v29
	ds_write_b64 v140, v[26:27] offset:8448
	v_max_f32_e32 v22, 0, v22
	v_max_f32_e32 v23, 0, v23
	v_max_f32_e32 v24, 0, v24
	v_max_f32_e32 v25, 0, v25
	v_pk_mul_f32 v[22:23], v[22:23], v[22:23]
	v_pk_mul_f32 v[24:25], v[24:25], v[24:25]
	v_cvt_pk_bf16_f32 v22, v22, v23
	v_cvt_pk_bf16_f32 v23, v24, v25
	ds_write_b64 v141, v[22:23] offset:256
	v_max_f32_e32 v18, 0, v18
	v_max_f32_e32 v19, 0, v19
	v_max_f32_e32 v20, 0, v20
	v_max_f32_e32 v21, 0, v21
	v_pk_mul_f32 v[18:19], v[18:19], v[18:19]
	v_pk_mul_f32 v[20:21], v[20:21], v[20:21]
	v_cvt_pk_bf16_f32 v18, v18, v19
	v_cvt_pk_bf16_f32 v19, v20, v21
	ds_write_b64 v141, v[18:19] offset:8448
	v_max_f32_e32 v14, 0, v14
	v_max_f32_e32 v15, 0, v15
	v_max_f32_e32 v16, 0, v16
	v_max_f32_e32 v17, 0, v17
	v_pk_mul_f32 v[14:15], v[14:15], v[14:15]
	v_pk_mul_f32 v[16:17], v[16:17], v[16:17]
	v_cvt_pk_bf16_f32 v14, v14, v15
	v_cvt_pk_bf16_f32 v15, v16, v17
	ds_write_b64 v142, v[14:15] offset:256
	v_max_f32_e32 v10, 0, v10
	v_max_f32_e32 v11, 0, v11
	v_max_f32_e32 v12, 0, v12
	v_max_f32_e32 v13, 0, v13
	v_pk_mul_f32 v[10:11], v[10:11], v[10:11]
	v_pk_mul_f32 v[12:13], v[12:13], v[12:13]
	v_cvt_pk_bf16_f32 v10, v10, v11
	v_cvt_pk_bf16_f32 v11, v12, v13
	ds_write_b64 v142, v[10:11] offset:8448
	v_max_f32_e32 v6, 0, v6
	v_max_f32_e32 v7, 0, v7
	v_max_f32_e32 v8, 0, v8
	v_max_f32_e32 v9, 0, v9
	v_pk_mul_f32 v[6:7], v[6:7], v[6:7]
	v_pk_mul_f32 v[8:9], v[8:9], v[8:9]
	v_cvt_pk_bf16_f32 v6, v6, v7
	v_cvt_pk_bf16_f32 v7, v8, v9
	ds_write_b64 v143, v[6:7] offset:256
	v_max_f32_e32 v2, 0, v2
	v_max_f32_e32 v3, 0, v3
	v_max_f32_e32 v4, 0, v4
	v_max_f32_e32 v5, 0, v5
	v_pk_mul_f32 v[2:3], v[2:3], v[2:3]
	v_pk_mul_f32 v[4:5], v[4:5], v[4:5]
	v_cvt_pk_bf16_f32 v2, v2, v3
	v_cvt_pk_bf16_f32 v3, v4, v5
	ds_write_b64 v143, v[2:3] offset:8448
	v_lshrrev_b32_e32 v0, 2, v188
	v_lshrrev_b32_e32 v130, 1, v0
	v_and_b32_e32 v0, 1, v0
	v_lshlrev_b32_e32 v0, 4, v0
	v_and_b32_e32 v131, 15, v189
	v_or_b32_e32 v0, v0, v131
	v_lshrrev_b32_e32 v131, 4, v187
	v_lshrrev_b32_e32 v144, 5, v189
	v_or_b32_e32 v131, v131, v144
	v_lshl_or_b32 v131, v131, 5, v130
	v_xor_b32_e32 v144, v0, v130
	v_lshlrev_b32_e32 v144, 4, v144
	v_lshl_or_b32 v144, v131, 9, v144
	v_add_u32_e32 v131, s91, v131
	v_lshlrev_b32_e32 v131, 15, v131
	v_lshl_add_u32 v131, v0, 4, v131
	s_lshl_b32 s0, s74, 1
	v_add_u32_e32 v145, s0, v131
	s_mov_b64 s[8:9], s[36:37]
	v_mov_b32_e32 v146, v144
	v_xor_b32_e32 v147, 32, v144
	v_xor_b32_e32 v148, 64, v144
	v_xor_b32_e32 v149, 96, v144
	v_xor_b32_e32 v150, 128, v144
	v_xor_b32_e32 v151, 160, v144
	v_xor_b32_e32 v152, 192, v144
	v_xor_b32_e32 v153, 224, v144
	s_waitcnt lgkmcnt(0)
	s_barrier
; __device__ __forceinline__ void epilogue(const Params& p, int mode, const float* resid, int r, int c, f32x4 v) {
;   if (mode == EPI_PROJ) {
;     if (r >= INW) return;
;     u32x2 pk = {pk2(v[0], v[1]), pk2(v[2], v[3])};
;     *reinterpret_cast<u32x2*>(WSP(u16, WS_PROJB) + (long)c * INWP + r) = pk;
; __device__ __forceinline__ void gemm_run(const Params& p, const u16* A1, const u16* Bt1, int M1, int N1, int K, int mode1,
;                                          const float* resid, u16* shm, const u16* A2, const u16* Bt2, int M2, int N2,
;                                          int mode2) {
;     ...
; #pragma unroll
;     for (int ai = 0; ai < 2; ++ai)
; #pragma unroll
;       for (int bj = 0; bj < 2; ++bj)
; #pragma unroll
;         for (int m = 0; m < 4; ++m)
; #pragma unroll
;           for (int n = 0; n < 2; ++n)
;             epilogue(p, mode, resid, brow + ai * HALF + wr * 64 + m * 16 + fq * 4, bcol + bj * HALF + wc * 32 + n * 16 + fr,
;                      acc[ai][bj][m][n]);
	ds_read_b128 v[2:5], v146 offset:64
	ds_read_b128 v[6:9], v147 offset:1088
	ds_read_b128 v[10:13], v148 offset:2112
	ds_read_b128 v[14:17], v149 offset:3136
	ds_read_b128 v[18:21], v150 offset:4160
	ds_read_b128 v[22:25], v151 offset:5184
	ds_read_b128 v[26:29], v152 offset:6208
	ds_read_b128 v[30:33], v153 offset:7232
	s_waitcnt lgkmcnt(7)
	global_store_dwordx4 v145, v[2:5], s[8:9] nt
	s_add_u32 s8, s8, 0x10000
	s_addc_u32 s9, s9, 0
	ds_read_b128 v[34:37], v146 offset:8256
	s_waitcnt lgkmcnt(7)
	global_store_dwordx4 v145, v[6:9], s[8:9] nt
	s_add_u32 s8, s8, 0x10000
	s_addc_u32 s9, s9, 0
	ds_read_b128 v[38:41], v147 offset:9280
	s_waitcnt lgkmcnt(7)
	global_store_dwordx4 v145, v[10:13], s[8:9] nt
	s_add_u32 s8, s8, 0x10000
	s_addc_u32 s9, s9, 0
	ds_read_b128 v[42:45], v148 offset:10304
	s_waitcnt lgkmcnt(7)
	global_store_dwordx4 v145, v[14:17], s[8:9] nt
	s_add_u32 s8, s8, 0x10000
	s_addc_u32 s9, s9, 0
	ds_read_b128 v[46:49], v149 offset:11328
	s_waitcnt lgkmcnt(7)
	global_store_dwordx4 v145, v[18:21], s[8:9] nt
	s_add_u32 s8, s8, 0x10000
	s_addc_u32 s9, s9, 0
	ds_read_b128 v[50:53], v150 offset:12352
	s_waitcnt lgkmcnt(7)
	global_store_dwordx4 v145, v[22:25], s[8:9] nt
	s_add_u32 s8, s8, 0x10000
	s_addc_u32 s9, s9, 0
	ds_read_b128 v[54:57], v151 offset:13376
	s_waitcnt lgkmcnt(7)
	global_store_dwordx4 v145, v[26:29], s[8:9] nt
	s_add_u32 s8, s8, 0x10000
	s_addc_u32 s9, s9, 0
	ds_read_b128 v[58:61], v152 offset:14400
	s_waitcnt lgkmcnt(7)
	global_store_dwordx4 v145, v[30:33], s[8:9] nt
	s_add_u32 s8, s8, 0x10000
	s_addc_u32 s9, s9, 0
	ds_read_b128 v[62:65], v153 offset:15424
	s_waitcnt lgkmcnt(7)
	global_store_dwordx4 v145, v[34:37], s[8:9] nt
	s_add_u32 s8, s8, 0x10000
	s_addc_u32 s9, s9, 0
	s_waitcnt lgkmcnt(6)
	global_store_dwordx4 v145, v[38:41], s[8:9] nt
	s_add_u32 s8, s8, 0x10000
	s_addc_u32 s9, s9, 0
	s_waitcnt lgkmcnt(5)
	global_store_dwordx4 v145, v[42:45], s[8:9] nt
	s_add_u32 s8, s8, 0x10000
	s_addc_u32 s9, s9, 0
	s_waitcnt lgkmcnt(4)
	global_store_dwordx4 v145, v[46:49], s[8:9] nt
	s_add_u32 s8, s8, 0x10000
	s_addc_u32 s9, s9, 0
	s_waitcnt lgkmcnt(3)
	global_store_dwordx4 v145, v[50:53], s[8:9] nt
	s_add_u32 s8, s8, 0x10000
	s_addc_u32 s9, s9, 0
	s_waitcnt lgkmcnt(2)
	global_store_dwordx4 v145, v[54:57], s[8:9] nt
	s_add_u32 s8, s8, 0x10000
	s_addc_u32 s9, s9, 0
	s_waitcnt lgkmcnt(1)
	global_store_dwordx4 v145, v[58:61], s[8:9] nt
	s_add_u32 s8, s8, 0x10000
	s_addc_u32 s9, s9, 0
	s_waitcnt lgkmcnt(0)
	global_store_dwordx4 v145, v[62:65], s[8:9] nt
	s_add_u32 s8, s8, 0x10000
	s_addc_u32 s9, s9, 0
	s_waitcnt lgkmcnt(0)
	s_barrier
	s_branch .LBB0_382
.Lepi0_start:
	v_add_u32_e32 v0, s74, v187
	v_or_b32_e32 v0, v0, v188
	v_or_b32_e32 v130, s91, v189
	v_lshlrev_b32_e32 v0, 1, v0
	v_mad_u32_u24 v136, v130, s95, v0
	v_add_u32_e32 v137, 0x6a000, v136
	v_add_u32_e32 v138, 0x350000, v136
	v_add_u32_e32 v139, 0x3ba000, v136
	v_cvt_pk_bf16_f32 v126, v126, v127
	v_cvt_pk_bf16_f32 v127, v128, v129
	global_store_dwordx2 v136, v[126:127], s[36:37] offset:0
	v_cvt_pk_bf16_f32 v122, v122, v123
	v_cvt_pk_bf16_f32 v123, v124, v125
	global_store_dwordx2 v137, v[122:123], s[36:37] offset:0
	v_cvt_pk_bf16_f32 v118, v118, v119
	v_cvt_pk_bf16_f32 v119, v120, v121
	global_store_dwordx2 v136, v[118:119], s[36:37] offset:32
	v_cvt_pk_bf16_f32 v114, v114, v115
	v_cvt_pk_bf16_f32 v115, v116, v117
	global_store_dwordx2 v137, v[114:115], s[36:37] offset:32
	v_cvt_pk_bf16_f32 v110, v110, v111
	v_cvt_pk_bf16_f32 v111, v112, v113
	global_store_dwordx2 v136, v[110:111], s[36:37] offset:64
	v_cvt_pk_bf16_f32 v106, v106, v107
	v_cvt_pk_bf16_f32 v107, v108, v109
	global_store_dwordx2 v137, v[106:107], s[36:37] offset:64
	v_cvt_pk_bf16_f32 v102, v102, v103
	v_cvt_pk_bf16_f32 v103, v104, v105
	global_store_dwordx2 v136, v[102:103], s[36:37] offset:96
	v_cvt_pk_bf16_f32 v98, v98, v99
	v_cvt_pk_bf16_f32 v99, v100, v101
	global_store_dwordx2 v137, v[98:99], s[36:37] offset:96
	v_cvt_pk_bf16_f32 v94, v94, v95
	v_cvt_pk_bf16_f32 v95, v96, v97
	global_store_dwordx2 v138, v[94:95], s[36:37] offset:0
	v_cvt_pk_bf16_f32 v90, v90, v91
	v_cvt_pk_bf16_f32 v91, v92, v93
	global_store_dwordx2 v139, v[90:91], s[36:37] offset:0
	v_cvt_pk_bf16_f32 v86, v86, v87
	v_cvt_pk_bf16_f32 v87, v88, v89
	global_store_dwordx2 v138, v[86:87], s[36:37] offset:32
	v_cvt_pk_bf16_f32 v82, v82, v83
	v_cvt_pk_bf16_f32 v83, v84, v85
	global_store_dwordx2 v139, v[82:83], s[36:37] offset:32
	v_cvt_pk_bf16_f32 v78, v78, v79
	v_cvt_pk_bf16_f32 v79, v80, v81
	global_store_dwordx2 v138, v[78:79], s[36:37] offset:64
	v_cvt_pk_bf16_f32 v74, v74, v75
	v_cvt_pk_bf16_f32 v75, v76, v77
	global_store_dwordx2 v139, v[74:75], s[36:37] offset:64
	v_cvt_pk_bf16_f32 v70, v70, v71
	v_cvt_pk_bf16_f32 v71, v72, v73
	global_store_dwordx2 v138, v[70:71], s[36:37] offset:96
	v_cvt_pk_bf16_f32 v66, v66, v67
	v_cvt_pk_bf16_f32 v67, v68, v69
	global_store_dwordx2 v139, v[66:67], s[36:37] offset:96
	v_cvt_pk_bf16_f32 v62, v62, v63
	v_cvt_pk_bf16_f32 v63, v64, v65
	global_store_dwordx2 v136, v[62:63], s[36:37] offset:256
	v_cvt_pk_bf16_f32 v58, v58, v59
	v_cvt_pk_bf16_f32 v59, v60, v61
	global_store_dwordx2 v137, v[58:59], s[36:37] offset:256
	v_cvt_pk_bf16_f32 v54, v54, v55
	v_cvt_pk_bf16_f32 v55, v56, v57
	global_store_dwordx2 v136, v[54:55], s[36:37] offset:288
	v_cvt_pk_bf16_f32 v50, v50, v51
	v_cvt_pk_bf16_f32 v51, v52, v53
	global_store_dwordx2 v137, v[50:51], s[36:37] offset:288
	v_cvt_pk_bf16_f32 v46, v46, v47
	v_cvt_pk_bf16_f32 v47, v48, v49
	global_store_dwordx2 v136, v[46:47], s[36:37] offset:320
	v_cvt_pk_bf16_f32 v42, v42, v43
	v_cvt_pk_bf16_f32 v43, v44, v45
	global_store_dwordx2 v137, v[42:43], s[36:37] offset:320
	v_cvt_pk_bf16_f32 v38, v38, v39
	v_cvt_pk_bf16_f32 v39, v40, v41
	global_store_dwordx2 v136, v[38:39], s[36:37] offset:352
	v_cvt_pk_bf16_f32 v34, v34, v35
	v_cvt_pk_bf16_f32 v35, v36, v37
	global_store_dwordx2 v137, v[34:35], s[36:37] offset:352
	v_cvt_pk_bf16_f32 v30, v30, v31
	v_cvt_pk_bf16_f32 v31, v32, v33
	global_store_dwordx2 v138, v[30:31], s[36:37] offset:256
	v_cvt_pk_bf16_f32 v26, v26, v27
	v_cvt_pk_bf16_f32 v27, v28, v29
	global_store_dwordx2 v139, v[26:27], s[36:37] offset:256
	v_cvt_pk_bf16_f32 v22, v22, v23
	v_cvt_pk_bf16_f32 v23, v24, v25
	global_store_dwordx2 v138, v[22:23], s[36:37] offset:288
	v_cvt_pk_bf16_f32 v18, v18, v19
	v_cvt_pk_bf16_f32 v19, v20, v21
	global_store_dwordx2 v139, v[18:19], s[36:37] offset:288
	v_cvt_pk_bf16_f32 v14, v14, v15
	v_cvt_pk_bf16_f32 v15, v16, v17
	global_store_dwordx2 v138, v[14:15], s[36:37] offset:320
	v_cvt_pk_bf16_f32 v10, v10, v11
	v_cvt_pk_bf16_f32 v11, v12, v13
	global_store_dwordx2 v139, v[10:11], s[36:37] offset:320
	v_cvt_pk_bf16_f32 v6, v6, v7
	v_cvt_pk_bf16_f32 v7, v8, v9
	global_store_dwordx2 v138, v[6:7], s[36:37] offset:352
	v_cvt_pk_bf16_f32 v2, v2, v3
	v_cvt_pk_bf16_f32 v3, v4, v5
	global_store_dwordx2 v139, v[2:3], s[36:37] offset:352
	s_branch .LBB0_382
; __device__ __forceinline__ void epilogue(const Params& p, int mode, const float* resid, int r, int c, f32x4 v) {
;     ...
;   } else if (mode == EPI_PROJ_T) {
;     const int b = r >> 11, t = r & 2047;
;     u16* tp;
;     if (c < OFF_RG) tp = WSP(u16, WS_RVT) + ((long)(b * 2048 + c - OFF_RV)) * 2048 + t;
;     else if (c < OFF_KW) tp = WSP(u16, WS_VST) + ((long)(b * 512 + c - OFF_VS)) * 2048 + t;
;     else tp = WSP(u16, WS_VWT) + ((long)(b * 512 + c - OFF_VW)) * 2048 + t;
;     *reinterpret_cast<u32x2*>(tp) = u32x2{pk2(v[0], v[1]), pk2(v[2], v[3])};
.Lepi6_start:
	s_lshr_b32 s0, s74, 11
	s_cmpk_lt_u32 s91, 0x1800
	s_cbranch_scc1 .Lepi6_rvt
	s_lshl_b32 s0, s0, 9
	s_cmpk_lt_u32 s91, 0x3000
	s_cbranch_scc1 .Lepi6_vst
	s_sub_i32 s0, s0, 0x3200
	s_mov_b64 s[8:9], s[48:49]
	s_branch .Lepi6_go
.Lepi6_vst:
	s_sub_i32 s0, s0, 0x2e00
	s_mov_b64 s[8:9], s[50:51]
	s_branch .Lepi6_go
.Lepi6_rvt:
	s_lshl_b32 s0, s0, 11
	s_sub_i32 s0, s0, 0x1000
	s_mov_b64 s[8:9], s[52:53]
.Lepi6_go:
	v_add_u32_e32 v0, s74, v187
	v_or_b32_e32 v0, v0, v188
	v_and_b32_e32 v0, 0x7ff, v0
	v_lshlrev_b32_e32 v0, 1, v0
	v_or_b32_e32 v130, s91, v189
	v_add_u32_e32 v130, s0, v130
	v_lshl_add_u32 v136, v130, 12, v0
	v_add_u32_e32 v137, 0x10000, v136
	v_add_u32_e32 v138, 0x80000, v136
	v_add_u32_e32 v139, 0x90000, v136
	v_cvt_pk_bf16_f32 v126, v126, v127
	v_cvt_pk_bf16_f32 v127, v128, v129
	global_store_dwordx2 v136, v[126:127], s[8:9] offset:0
	v_cvt_pk_bf16_f32 v122, v122, v123
	v_cvt_pk_bf16_f32 v123, v124, v125
	global_store_dwordx2 v137, v[122:123], s[8:9] offset:0
	v_cvt_pk_bf16_f32 v118, v118, v119
	v_cvt_pk_bf16_f32 v119, v120, v121
	global_store_dwordx2 v136, v[118:119], s[8:9] offset:32
	v_cvt_pk_bf16_f32 v114, v114, v115
	v_cvt_pk_bf16_f32 v115, v116, v117
	global_store_dwordx2 v137, v[114:115], s[8:9] offset:32
	v_cvt_pk_bf16_f32 v110, v110, v111
	v_cvt_pk_bf16_f32 v111, v112, v113
	global_store_dwordx2 v136, v[110:111], s[8:9] offset:64
	v_cvt_pk_bf16_f32 v106, v106, v107
	v_cvt_pk_bf16_f32 v107, v108, v109
	global_store_dwordx2 v137, v[106:107], s[8:9] offset:64
	v_cvt_pk_bf16_f32 v102, v102, v103
	v_cvt_pk_bf16_f32 v103, v104, v105
	global_store_dwordx2 v136, v[102:103], s[8:9] offset:96
	v_cvt_pk_bf16_f32 v98, v98, v99
	v_cvt_pk_bf16_f32 v99, v100, v101
	global_store_dwordx2 v137, v[98:99], s[8:9] offset:96
	v_cvt_pk_bf16_f32 v94, v94, v95
	v_cvt_pk_bf16_f32 v95, v96, v97
	global_store_dwordx2 v138, v[94:95], s[8:9] offset:0
	v_cvt_pk_bf16_f32 v90, v90, v91
	v_cvt_pk_bf16_f32 v91, v92, v93
	global_store_dwordx2 v139, v[90:91], s[8:9] offset:0
	v_cvt_pk_bf16_f32 v86, v86, v87
	v_cvt_pk_bf16_f32 v87, v88, v89
	global_store_dwordx2 v138, v[86:87], s[8:9] offset:32
	v_cvt_pk_bf16_f32 v82, v82, v83
	v_cvt_pk_bf16_f32 v83, v84, v85
	global_store_dwordx2 v139, v[82:83], s[8:9] offset:32
	v_cvt_pk_bf16_f32 v78, v78, v79
	v_cvt_pk_bf16_f32 v79, v80, v81
	global_store_dwordx2 v138, v[78:79], s[8:9] offset:64
	v_cvt_pk_bf16_f32 v74, v74, v75
	v_cvt_pk_bf16_f32 v75, v76, v77
	global_store_dwordx2 v139, v[74:75], s[8:9] offset:64
	v_cvt_pk_bf16_f32 v70, v70, v71
	v_cvt_pk_bf16_f32 v71, v72, v73
	global_store_dwordx2 v138, v[70:71], s[8:9] offset:96
	v_cvt_pk_bf16_f32 v66, v66, v67
	v_cvt_pk_bf16_f32 v67, v68, v69
	global_store_dwordx2 v139, v[66:67], s[8:9] offset:96
	v_cvt_pk_bf16_f32 v62, v62, v63
	v_cvt_pk_bf16_f32 v63, v64, v65
	global_store_dwordx2 v136, v[62:63], s[8:9] offset:256
	v_cvt_pk_bf16_f32 v58, v58, v59
	v_cvt_pk_bf16_f32 v59, v60, v61
	global_store_dwordx2 v137, v[58:59], s[8:9] offset:256
	v_cvt_pk_bf16_f32 v54, v54, v55
	v_cvt_pk_bf16_f32 v55, v56, v57
	global_store_dwordx2 v136, v[54:55], s[8:9] offset:288
	v_cvt_pk_bf16_f32 v50, v50, v51
	v_cvt_pk_bf16_f32 v51, v52, v53
	global_store_dwordx2 v137, v[50:51], s[8:9] offset:288
	v_cvt_pk_bf16_f32 v46, v46, v47
	v_cvt_pk_bf16_f32 v47, v48, v49
	global_store_dwordx2 v136, v[46:47], s[8:9] offset:320
	v_cvt_pk_bf16_f32 v42, v42, v43
	v_cvt_pk_bf16_f32 v43, v44, v45
	global_store_dwordx2 v137, v[42:43], s[8:9] offset:320
	v_cvt_pk_bf16_f32 v38, v38, v39
	v_cvt_pk_bf16_f32 v39, v40, v41
	global_store_dwordx2 v136, v[38:39], s[8:9] offset:352
	v_cvt_pk_bf16_f32 v34, v34, v35
	v_cvt_pk_bf16_f32 v35, v36, v37
	global_store_dwordx2 v137, v[34:35], s[8:9] offset:352
	v_cvt_pk_bf16_f32 v30, v30, v31
	v_cvt_pk_bf16_f32 v31, v32, v33
	global_store_dwordx2 v138, v[30:31], s[8:9] offset:256
	v_cvt_pk_bf16_f32 v26, v26, v27
	v_cvt_pk_bf16_f32 v27, v28, v29
	global_store_dwordx2 v139, v[26:27], s[8:9] offset:256
	v_cvt_pk_bf16_f32 v22, v22, v23
	v_cvt_pk_bf16_f32 v23, v24, v25
	global_store_dwordx2 v138, v[22:23], s[8:9] offset:288
	v_cvt_pk_bf16_f32 v18, v18, v19
	v_cvt_pk_bf16_f32 v19, v20, v21
	global_store_dwordx2 v139, v[18:19], s[8:9] offset:288
	v_cvt_pk_bf16_f32 v14, v14, v15
	v_cvt_pk_bf16_f32 v15, v16, v17
	global_store_dwordx2 v138, v[14:15], s[8:9] offset:320
	v_cvt_pk_bf16_f32 v10, v10, v11
	v_cvt_pk_bf16_f32 v11, v12, v13
	global_store_dwordx2 v139, v[10:11], s[8:9] offset:320
	v_cvt_pk_bf16_f32 v6, v6, v7
	v_cvt_pk_bf16_f32 v7, v8, v9
	global_store_dwordx2 v138, v[6:7], s[8:9] offset:352
	v_cvt_pk_bf16_f32 v2, v2, v3
	v_cvt_pk_bf16_f32 v3, v4, v5
	global_store_dwordx2 v139, v[2:3], s[8:9] offset:352
	s_branch .LBB0_382
